# S5 scan recurrence rewritten as fused FMAs (8 VALU per step instead of 10) on top of saddr up-GEMM
# speedup vs baseline: 1.0041x; 1.0041x over previous
; #define LAS __attribute__((address_space(3)))
; __device__ __forceinline__ unsigned cvt_pk_bf16(float lo, float hi) { unsigned r; asm volatile("v_cvt_pk_bf16_f32 %0, %1, %2" : "=v"(r) : "v"(lo), "v"(hi)); return r; }
; __device__ __forceinline__ void s5_phase(const Ctx& C, const bf16_t* U, bf16_t* Gout, const float* ABAR, const bf16_t* BB, const bf16_t* CM, const float* Dsk) {
;     ...
;                     const LAS unsigned char* src = bub + (i & 1) * 4096 + lane * 16;
;                     LAS unsigned char* dst = hb + (i & 1) * (S5_SUB * S5_HP) + lane * 4;
;                     u32x4 bq[S5_SUB / 4];
; #pragma unroll
;                     for (int q = 0; q < S5_SUB / 4; ++q) bq[q] = *(const LAS u32x4*)(src + q * 1024);
; #pragma unroll
;                     for (int t = 0; t < S5_SUB; ++t) {
;                         const unsigned bw = bq[t >> 2][t & 3];
;                         const float nr = ab.x * hr - ab.y * hi + bflo(bw), ni = ab.x * hi + ab.y * hr + bfhi(bw);
;                         hr = nr; hi = ni;
;                         *(LAS unsigned*)(dst + t * S5_HP) = cvt_pk_bf16(hr, hi);
;                     }
.LBB0_179:
	v_lshl_add_u32 v3, s22, 12, v81
	ds_read_b128 v[10:13], v3
	ds_read_b128 v[14:17], v3 offset:1024
	ds_read_b128 v[18:21], v3 offset:2048
	ds_read_b128 v[22:25], v3 offset:3072
	v_mul_f32_e32 v26, v0, v9
	v_mul_f32_e32 v27, v0, v8
	v_fma_f32 v26, -v1, v8, v26
	v_fmac_f32_e32 v27, v1, v9
	s_mulk_i32 s22, 0x1100
	s_waitcnt lgkmcnt(0)
	v_lshlrev_b32_e32 v4, 16, v10
	v_and_b32_e32 v5, 0xffff0000, v10
	v_add_u32_e32 v3, s22, v82
	v_add_f32_e32 v26, v26, v4
	v_add_f32_e32 v27, v27, v5
	v_cvt_pk_bf16_f32 v4, v26, v27
	ds_write_b32 v3, v4
	v_lshlrev_b32_e32 v9, 16, v11
	v_and_b32_e32 v8, 0xffff0000, v11
	v_fma_f32 v9, -v1, v27, v9
	v_fmac_f32_e32 v8, v1, v26
	v_fmac_f32_e32 v9, v0, v26
	v_fmac_f32_e32 v8, v0, v27
	v_cvt_pk_bf16_f32 v5, v9, v8
	ds_write_b32 v3, v5 offset:272
	v_lshlrev_b32_e32 v26, 16, v12
	v_and_b32_e32 v27, 0xffff0000, v12
	v_fma_f32 v26, -v1, v8, v26
	v_fmac_f32_e32 v27, v1, v9
	v_fmac_f32_e32 v26, v0, v9
	v_fmac_f32_e32 v27, v0, v8
	v_cvt_pk_bf16_f32 v4, v26, v27
	ds_write_b32 v3, v4 offset:544
	v_lshlrev_b32_e32 v9, 16, v13
	v_and_b32_e32 v8, 0xffff0000, v13
	v_fma_f32 v9, -v1, v27, v9
	v_fmac_f32_e32 v8, v1, v26
	v_fmac_f32_e32 v9, v0, v26
	v_fmac_f32_e32 v8, v0, v27
	v_cvt_pk_bf16_f32 v5, v9, v8
	ds_write_b32 v3, v5 offset:816
	v_lshlrev_b32_e32 v26, 16, v14
	v_and_b32_e32 v27, 0xffff0000, v14
	v_fma_f32 v26, -v1, v8, v26
	v_fmac_f32_e32 v27, v1, v9
	v_fmac_f32_e32 v26, v0, v9
	v_fmac_f32_e32 v27, v0, v8
	v_cvt_pk_bf16_f32 v4, v26, v27
	ds_write_b32 v3, v4 offset:1088
	v_lshlrev_b32_e32 v9, 16, v15
	v_and_b32_e32 v8, 0xffff0000, v15
	v_fma_f32 v9, -v1, v27, v9
	v_fmac_f32_e32 v8, v1, v26
	v_fmac_f32_e32 v9, v0, v26
	v_fmac_f32_e32 v8, v0, v27
	v_cvt_pk_bf16_f32 v5, v9, v8
	ds_write_b32 v3, v5 offset:1360
	v_lshlrev_b32_e32 v26, 16, v16
	v_and_b32_e32 v27, 0xffff0000, v16
	v_fma_f32 v26, -v1, v8, v26
	v_fmac_f32_e32 v27, v1, v9
	v_fmac_f32_e32 v26, v0, v9
	v_fmac_f32_e32 v27, v0, v8
	v_cvt_pk_bf16_f32 v4, v26, v27
	ds_write_b32 v3, v4 offset:1632
	v_lshlrev_b32_e32 v9, 16, v17
	v_and_b32_e32 v8, 0xffff0000, v17
	v_fma_f32 v9, -v1, v27, v9
	v_fmac_f32_e32 v8, v1, v26
	v_fmac_f32_e32 v9, v0, v26
	v_fmac_f32_e32 v8, v0, v27
	v_cvt_pk_bf16_f32 v5, v9, v8
	ds_write_b32 v3, v5 offset:1904
	v_lshlrev_b32_e32 v26, 16, v18
	v_and_b32_e32 v27, 0xffff0000, v18
	v_fma_f32 v26, -v1, v8, v26
	v_fmac_f32_e32 v27, v1, v9
	v_fmac_f32_e32 v26, v0, v9
	v_fmac_f32_e32 v27, v0, v8
	v_cvt_pk_bf16_f32 v4, v26, v27
	ds_write_b32 v3, v4 offset:2176
	v_lshlrev_b32_e32 v9, 16, v19
	v_and_b32_e32 v8, 0xffff0000, v19
	v_fma_f32 v9, -v1, v27, v9
	v_fmac_f32_e32 v8, v1, v26
	v_fmac_f32_e32 v9, v0, v26
	v_fmac_f32_e32 v8, v0, v27
	v_cvt_pk_bf16_f32 v5, v9, v8
	ds_write_b32 v3, v5 offset:2448
	v_lshlrev_b32_e32 v26, 16, v20
	v_and_b32_e32 v27, 0xffff0000, v20
	v_fma_f32 v26, -v1, v8, v26
	v_fmac_f32_e32 v27, v1, v9
	v_fmac_f32_e32 v26, v0, v9
	v_fmac_f32_e32 v27, v0, v8
	v_cvt_pk_bf16_f32 v4, v26, v27
	ds_write_b32 v3, v4 offset:2720
	v_lshlrev_b32_e32 v9, 16, v21
	v_and_b32_e32 v8, 0xffff0000, v21
	v_fma_f32 v9, -v1, v27, v9
	v_fmac_f32_e32 v8, v1, v26
	v_fmac_f32_e32 v9, v0, v26
	v_fmac_f32_e32 v8, v0, v27
	v_cvt_pk_bf16_f32 v5, v9, v8
	ds_write_b32 v3, v5 offset:2992
	v_lshlrev_b32_e32 v26, 16, v22
	v_and_b32_e32 v27, 0xffff0000, v22
	v_fma_f32 v26, -v1, v8, v26
	v_fmac_f32_e32 v27, v1, v9
	v_fmac_f32_e32 v26, v0, v9
	v_fmac_f32_e32 v27, v0, v8
	v_cvt_pk_bf16_f32 v4, v26, v27
	ds_write_b32 v3, v4 offset:3264
	v_lshlrev_b32_e32 v9, 16, v23
	v_and_b32_e32 v8, 0xffff0000, v23
	v_fma_f32 v9, -v1, v27, v9
	v_fmac_f32_e32 v8, v1, v26
	v_fmac_f32_e32 v9, v0, v26
	v_fmac_f32_e32 v8, v0, v27
	v_cvt_pk_bf16_f32 v5, v9, v8
	ds_write_b32 v3, v5 offset:3536
	v_lshlrev_b32_e32 v26, 16, v24
	v_and_b32_e32 v27, 0xffff0000, v24
	v_fma_f32 v26, -v1, v8, v26
	v_fmac_f32_e32 v27, v1, v9
	v_fmac_f32_e32 v26, v0, v9
	v_fmac_f32_e32 v27, v0, v8
	v_cvt_pk_bf16_f32 v4, v26, v27
	ds_write_b32 v3, v4 offset:3808
	v_lshlrev_b32_e32 v9, 16, v25
	v_and_b32_e32 v8, 0xffff0000, v25
	v_fma_f32 v9, -v1, v27, v9
	v_fmac_f32_e32 v8, v1, v26
	v_fmac_f32_e32 v9, v0, v26
	v_fmac_f32_e32 v8, v0, v27
	v_cvt_pk_bf16_f32 v5, v9, v8
	ds_write_b32 v3, v5 offset:4080
	s_cmpk_gt_u32 s39, 0xf8
	s_mov_b64 s[22:23], -1
	s_cbranch_scc0 .LBB0_181
	s_waitcnt vmcnt(0)
	s_mov_b64 s[22:23], 0
